# GLA step 2a: never-taken denormal/inf handling of the log2 expansion removed (argument is always in (1,2]); bit-identical results
# speedup vs baseline: 1.0048x; 1.0048x over previous
; #define LAS __attribute__((address_space(3)))
; #define MFMA16(a, b, c) __builtin_amdgcn_mfma_f32_16x16x32_bf16((a), (b), (c), 0, 0, 0)
; template <bool PASS2>
; __device__ __forceinline__ void gla_pass(LAS unsigned char* lds, const Params& p, int layer) {
;     ...
;                 for (int m = 0; m < 4; ++m) {
;                     const bf16x8 A = *(LAS bf16x8*)(lds + SLR + (m * 16 + fr) * 64 + fq * 16);
;                     f32x4 xx = (f32x4){0.f, 0.f, 0.f, 0.f};
;                     xx = MFMA16(A, wB1, xx); xx = MFMA16(A, wB2, xx);
; #pragma unroll
;                     for (int jj = 0; jj < 4; ++jj) { const float x = xx[jj] + biasx; const float ls = fminf(x, 0.f) - __logf(1.f + __expf(-fabsf(x)));
;                         *(LAS float*)(lds + SX + ((m * 16 + 4 * fq + jj) * 132 + wid * 16 + fr) * 4) = ls * 0.0625f; }
;                 }
;                 if (PASS2) {
; #pragma unroll
;                     for (int it = 0; it < 2; ++it) { const int pi = tid + 512 * it, row = pi >> 4, seg = pi & 15; *(LAS u32x4*)(lds + SQ + row * 272 + seg * 16) = rq[it]; } }
;                 __syncthreads();
;                 float c0[8], c1[8];
; #pragma unroll
;                 for (int e = 0; e < 8; ++e) { const f32x2 t2 = *(LAS f32x2*)(lds + SX + ((wid * 8 + e) * 132 + dk0) * 4); c0[e] = t2.x; c1[e] = t2.y; }
;                 if (dir == 0) {
; #pragma unroll
;                     for (int e = 1; e < 8; ++e) { c0[e] += c0[e - 1]; c1[e] += c1[e - 1]; }
;                 } else {
; #pragma unroll
;                     for (int e = 6; e >= 0; --e) { c0[e] += c0[e + 1]; c1[e] += c1[e + 1]; }
.LBB0_456:
	v_add_u32_e32 v111, 0, v110
	ds_read_b128 v[112:115], v111
	s_add_i32 s4, s4, -1
	v_add_u32_e32 v110, 0x400, v110
	s_cmp_lg_u32 s4, 0
	s_waitcnt lgkmcnt(0)
	v_mfma_f32_16x16x32_bf16 v[166:169], v[112:115], v[12:15], 0
	v_mfma_f32_16x16x32_bf16 v[112:115], v[112:115], v[16:19], v[166:169]
	s_nop 7
	v_add_f32_e32 v111, v135, v112
	v_min_f32_e32 v112, 0, v111
	v_mul_f32_e64 v111, |v111|, s79
	v_exp_f32_e32 v111, v111
	s_nop 0
	v_add_f32_e32 v111, 1.0, v111
	v_log_f32_e32 v111, v111
	s_nop 0
	v_mul_f32_e32 v137, 0x3f317217, v111
	v_fma_f32 v137, v111, s81, -v137
	v_fmac_f32_e32 v137, 0x3377d1cf, v111
	v_fmac_f32_e32 v137, 0x3f317217, v111
	v_sub_f32_e32 v111, v112, v137
	v_mul_f32_e32 v111, 0x3d800000, v111
	v_add_u32_e32 v112, 0, v109
	ds_write_b32 v112, v111
	v_add_f32_e32 v111, v135, v113
	v_min_f32_e32 v112, 0, v111
	v_mul_f32_e64 v111, |v111|, s79
	v_exp_f32_e32 v111, v111
	v_add_u32_e32 v109, 0x2100, v109
	v_add_f32_e32 v111, 1.0, v111
	v_log_f32_e32 v111, v111
	s_nop 0
	v_mul_f32_e32 v113, 0x3f317217, v111
	v_fma_f32 v113, v111, s81, -v113
	v_fmac_f32_e32 v113, 0x3377d1cf, v111
	v_fmac_f32_e32 v113, 0x3f317217, v111
	v_sub_f32_e32 v111, v112, v113
	v_add_u32_e32 v112, 0, v108
	v_mul_f32_e32 v111, 0x3d800000, v111
	v_add_u32_e32 v113, 0x15010, v112
	ds_write_b32 v113, v111
	v_add_f32_e32 v111, v135, v114
	v_min_f32_e32 v113, 0, v111
	v_mul_f32_e64 v111, |v111|, s79
	v_exp_f32_e32 v111, v111
	v_add_u32_e32 v108, 0x2100, v108
	v_add_f32_e32 v111, 1.0, v111
	v_log_f32_e32 v111, v111
	s_nop 0
	v_mul_f32_e32 v114, 0x3f317217, v111
	v_fma_f32 v114, v111, s81, -v114
	v_fmac_f32_e32 v114, 0x3377d1cf, v111
	v_fmac_f32_e32 v114, 0x3f317217, v111
	v_sub_f32_e32 v111, v113, v114
	v_mul_f32_e32 v111, 0x3d800000, v111
	v_add_u32_e32 v113, 0x15220, v112
	ds_write_b32 v113, v111
	v_add_f32_e32 v111, v135, v115
	v_min_f32_e32 v113, 0, v111
	v_mul_f32_e64 v111, |v111|, s79
	v_exp_f32_e32 v111, v111
	v_add_u32_e32 v112, 0x15430, v112
	v_add_f32_e32 v111, 1.0, v111
	v_log_f32_e32 v111, v111
	s_nop 0
	v_mul_f32_e32 v114, 0x3f317217, v111
	v_fma_f32 v114, v111, s81, -v114
	v_fmac_f32_e32 v114, 0x3377d1cf, v111
	v_fmac_f32_e32 v114, 0x3f317217, v111
	v_sub_f32_e32 v111, v113, v114
	v_mul_f32_e32 v111, 0x3d800000, v111
	ds_write_b32 v112, v111
	s_cbranch_scc1 .LBB0_456
	v_add_u32_e32 v108, v185, v191
	s_waitcnt vmcnt(7)
	ds_write_b128 v108, v[104:107]
	v_add_u32_e32 v104, v185, v192
	s_waitcnt vmcnt(6)
	ds_write_b128 v104, v[100:103]
	s_waitcnt lgkmcnt(0)
	s_barrier
	ds_read_b64 v[100:101], v197
	ds_read_b64 v[102:103], v198
	ds_read_b64 v[104:105], v199
	ds_read_b64 v[106:107], v200
	ds_read_b64 v[108:109], v201
	ds_read_b64 v[110:111], v202
	ds_read_b64 v[112:113], v203
	ds_read_b64 v[166:167], v204
	v_cndmask_b32_e64 v114, 0, 1, s[86:87]
	v_cmp_ne_u32_e64 s[66:67], 1, v114
	s_andn2_b64 vcc, exec, s[86:87]
	s_mov_b64 s[4:5], -1
	s_cbranch_vccnz .LBB0_459
	s_waitcnt lgkmcnt(0)
	v_pk_add_f32 v[168:169], v[112:113], v[166:167]
	s_mov_b64 s[4:5], 0
	v_pk_add_f32 v[170:171], v[110:111], v[168:169]
	s_nop 0
	v_pk_add_f32 v[172:173], v[108:109], v[170:171]
	s_nop 0
	v_pk_add_f32 v[174:175], v[106:107], v[172:173]
	s_nop 0
	v_pk_add_f32 v[176:177], v[104:105], v[174:175]
	s_nop 0
	v_pk_add_f32 v[178:179], v[102:103], v[176:177]
	s_nop 0
	v_pk_add_f32 v[180:181], v[100:101], v[178:179]
